# speedup vs baseline: 1.0043x; 1.0043x over previous
; __device__ __forceinline__ float fdiv(float a, float b) { return a * __builtin_amdgcn_rcpf(b); }
; __device__ __forceinline__ void gemm_tile(const Params& P, const GArgs& ga, const TileDesc& td, int wid_s) {
;     ...
;   if (mode == M_GU) {
;     LOAD_RSV
;     unsigned* __restrict__ G = reinterpret_cast<unsigned*>(WSU(G) + (size_t)rbase * FF + (bcol >> 1) + (x4 >> 1));
;     static_for<32>([&](auto ic) __attribute__((always_inline)) {
;       EPI_IDX;
;       const float rs = rsv[idx];
;       float g0 = rs * acc[ai][0][m][0][j], u0 = rs * acc[ai][0][m][1][j];
;       float g1 = rs * acc[ai][1][m][0][j], u1 = rs * acc[ai][1][m][1][j];
;       __builtin_nontemporal_store(pack2(fdiv(g0 * u0, 1.f + __expf(-g0)), fdiv(g1 * u1, 1.f + __expf(-g1))), G + (size_t)rl * (FF / 2));
.LBB0_748:
	s_and_b64 vcc, exec, s[84:85]
	s_cbranch_vccz .LBB0_290
	v_lshl_add_u64 v[194:195], v[166:167], 2, s[72:73]
	global_load_dwordx4 v[130:133], v[194:195], off
	global_load_dwordx4 v[134:137], v[194:195], off offset:64
	global_load_dwordx4 v[138:141], v[194:195], off offset:128
	global_load_dwordx4 v[142:145], v[194:195], off offset:192
	global_load_dwordx4 v[146:149], v[194:195], off offset:512
	global_load_dwordx4 v[150:153], v[194:195], off offset:576
	global_load_dwordx4 v[154:157], v[194:195], off offset:640
	global_load_dwordx4 v[158:161], v[194:195], off offset:704
	v_and_b32_e32 v196, 15, v200
	v_and_b32_e32 v197, 0xc0, v200
	v_lshl_or_b32 v196, v196, 2, v197
	s_lshl_b32 s0, s15, 8
	v_mov_b32_e32 v197, 0x2c00
	v_mad_u32_u24 v196, v166, v197, v196
	v_mov_b32_e32 v198, s17
	v_add_u32_e32 v196, s0, v196
	s_waitcnt vmcnt(7)
	v_fmamk_f32 v130, v130, 0x3a000000, v198
	v_fmamk_f32 v131, v131, 0x3a000000, v198
	v_fmamk_f32 v132, v132, 0x3a000000, v198
	v_fmamk_f32 v133, v133, 0x3a000000, v198
	v_rsq_f32_e32 v162, v130
	v_rsq_f32_e32 v163, v131
	v_rsq_f32_e32 v164, v132
	v_rsq_f32_e32 v165, v133
	s_waitcnt vmcnt(6)
	v_fmamk_f32 v134, v134, 0x3a000000, v198
	v_fmamk_f32 v135, v135, 0x3a000000, v198
	v_fmamk_f32 v136, v136, 0x3a000000, v198
	v_fmamk_f32 v137, v137, 0x3a000000, v198
	v_rsq_f32_e32 v166, v134
	v_rsq_f32_e32 v167, v135
	v_rsq_f32_e32 v168, v136
	v_rsq_f32_e32 v169, v137
	v_mul_f32_e32 v162, 0xbfb8aa3b, v162
	v_mul_f32_e32 v163, 0xbfb8aa3b, v163
	v_mul_f32_e32 v164, 0xbfb8aa3b, v164
	v_mul_f32_e32 v165, 0xbfb8aa3b, v165
	s_waitcnt vmcnt(5)
	v_fmamk_f32 v138, v138, 0x3a000000, v198
	v_fmamk_f32 v139, v139, 0x3a000000, v198
	v_fmamk_f32 v140, v140, 0x3a000000, v198
	v_fmamk_f32 v141, v141, 0x3a000000, v198
	v_rsq_f32_e32 v170, v138
	v_rsq_f32_e32 v171, v139
	v_rsq_f32_e32 v172, v140
	v_rsq_f32_e32 v173, v141
	v_mul_f32_e32 v166, 0xbfb8aa3b, v166
	v_mul_f32_e32 v167, 0xbfb8aa3b, v167
	v_mul_f32_e32 v168, 0xbfb8aa3b, v168
	v_mul_f32_e32 v169, 0xbfb8aa3b, v169
	s_waitcnt vmcnt(4)
	v_fmamk_f32 v142, v142, 0x3a000000, v198
	v_fmamk_f32 v143, v143, 0x3a000000, v198
	v_fmamk_f32 v144, v144, 0x3a000000, v198
	v_fmamk_f32 v145, v145, 0x3a000000, v198
	v_rsq_f32_e32 v174, v142
	v_rsq_f32_e32 v175, v143
	v_rsq_f32_e32 v176, v144
	v_rsq_f32_e32 v177, v145
	v_mul_f32_e32 v170, 0xbfb8aa3b, v170
	v_mul_f32_e32 v171, 0xbfb8aa3b, v171
	v_mul_f32_e32 v172, 0xbfb8aa3b, v172
	v_mul_f32_e32 v173, 0xbfb8aa3b, v173
	s_waitcnt vmcnt(3)
	v_fmamk_f32 v146, v146, 0x3a000000, v198
	v_fmamk_f32 v147, v147, 0x3a000000, v198
	v_fmamk_f32 v148, v148, 0x3a000000, v198
	v_fmamk_f32 v149, v149, 0x3a000000, v198
	v_rsq_f32_e32 v178, v146
	v_rsq_f32_e32 v179, v147
	v_rsq_f32_e32 v180, v148
	v_rsq_f32_e32 v181, v149
	v_mul_f32_e32 v174, 0xbfb8aa3b, v174
	v_mul_f32_e32 v175, 0xbfb8aa3b, v175
	v_mul_f32_e32 v176, 0xbfb8aa3b, v176
	v_mul_f32_e32 v177, 0xbfb8aa3b, v177
	s_waitcnt vmcnt(2)
	v_fmamk_f32 v150, v150, 0x3a000000, v198
	v_fmamk_f32 v151, v151, 0x3a000000, v198
	v_fmamk_f32 v152, v152, 0x3a000000, v198
	v_fmamk_f32 v153, v153, 0x3a000000, v198
	v_rsq_f32_e32 v182, v150
	v_rsq_f32_e32 v183, v151
	v_rsq_f32_e32 v184, v152
	v_rsq_f32_e32 v185, v153
	v_mul_f32_e32 v178, 0xbfb8aa3b, v178
	v_mul_f32_e32 v179, 0xbfb8aa3b, v179
	v_mul_f32_e32 v180, 0xbfb8aa3b, v180
	v_mul_f32_e32 v181, 0xbfb8aa3b, v181
	s_waitcnt vmcnt(1)
	v_fmamk_f32 v154, v154, 0x3a000000, v198
	v_fmamk_f32 v155, v155, 0x3a000000, v198
	v_fmamk_f32 v156, v156, 0x3a000000, v198
	v_fmamk_f32 v157, v157, 0x3a000000, v198
	v_rsq_f32_e32 v186, v154
	v_rsq_f32_e32 v187, v155
	v_rsq_f32_e32 v188, v156
	v_rsq_f32_e32 v189, v157
	v_mul_f32_e32 v182, 0xbfb8aa3b, v182
	v_mul_f32_e32 v183, 0xbfb8aa3b, v183
	v_mul_f32_e32 v184, 0xbfb8aa3b, v184
	v_mul_f32_e32 v185, 0xbfb8aa3b, v185
	s_waitcnt vmcnt(0)
	v_fmamk_f32 v158, v158, 0x3a000000, v198
	v_fmamk_f32 v159, v159, 0x3a000000, v198
	v_fmamk_f32 v160, v160, 0x3a000000, v198
	v_fmamk_f32 v161, v161, 0x3a000000, v198
	v_rsq_f32_e32 v190, v158
	v_rsq_f32_e32 v191, v159
	v_rsq_f32_e32 v192, v160
	v_rsq_f32_e32 v193, v161
	v_mul_f32_e32 v186, 0xbfb8aa3b, v186
	v_mul_f32_e32 v187, 0xbfb8aa3b, v187
	v_mul_f32_e32 v188, 0xbfb8aa3b, v188
	v_mul_f32_e32 v189, 0xbfb8aa3b, v189
	s_nop 0
	v_mul_f32_e32 v190, 0xbfb8aa3b, v190
	v_mul_f32_e32 v191, 0xbfb8aa3b, v191
	v_mul_f32_e32 v192, 0xbfb8aa3b, v192
	v_mul_f32_e32 v193, 0xbfb8aa3b, v193
	v_mul_f32_e32 v204, v114, v162
	v_mul_f32_e32 v205, v126, v162
	v_mul_f32_e32 v206, v115, v163
	v_mul_f32_e32 v207, v127, v163
	v_mul_f32_e32 v208, v116, v164
	v_mul_f32_e32 v209, v128, v164
	v_mul_f32_e32 v210, v117, v165
	v_mul_f32_e32 v211, v129, v165
	v_exp_f32_e32 v204, v204
	v_mul_f32_e32 v212, v114, v118
	v_exp_f32_e32 v205, v205
	v_mul_f32_e32 v213, v126, v122
	v_exp_f32_e32 v206, v206
	v_mul_f32_e32 v214, v115, v119
	v_exp_f32_e32 v207, v207
	v_mul_f32_e32 v215, v127, v123
	v_exp_f32_e32 v208, v208
	v_mul_f32_e32 v216, v116, v120
	v_exp_f32_e32 v209, v209
	v_mul_f32_e32 v217, v128, v124
	v_exp_f32_e32 v210, v210
	v_mul_f32_e32 v218, v117, v121
	v_exp_f32_e32 v211, v211
	v_mul_f32_e32 v219, v129, v125
	v_fma_f32 v204, v204, v130, v130
	v_fma_f32 v205, v205, v130, v130
	v_fma_f32 v206, v206, v131, v131
	v_fma_f32 v207, v207, v131, v131
	v_fma_f32 v208, v208, v132, v132
	v_fma_f32 v209, v209, v132, v132
	v_fma_f32 v210, v210, v133, v133
	v_fma_f32 v211, v211, v133, v133
	v_rcp_f32_e32 v204, v204
	v_mul_f32_e32 v232, v98, v166
	v_rcp_f32_e32 v205, v205
	v_mul_f32_e32 v233, v110, v166
	v_rcp_f32_e32 v206, v206
	v_mul_f32_e32 v234, v99, v167
	v_rcp_f32_e32 v207, v207
	v_mul_f32_e32 v235, v111, v167
	v_rcp_f32_e32 v208, v208
; __device__ __forceinline__ float fdiv(float a, float b) { return a * __builtin_amdgcn_rcpf(b); }
; __device__ __forceinline__ void gemm_tile(const Params& P, const GArgs& ga, const TileDesc& td, int wid_s) {
;     ...
;     static_for<32>([&](auto ic) __attribute__((always_inline)) {
;       EPI_IDX;
;       const float rs = rsv[idx];
;       float g0 = rs * acc[ai][0][m][0][j], u0 = rs * acc[ai][0][m][1][j];
;       float g1 = rs * acc[ai][1][m][0][j], u1 = rs * acc[ai][1][m][1][j];
;       __builtin_nontemporal_store(pack2(fdiv(g0 * u0, 1.f + __expf(-g0)), fdiv(g1 * u1, 1.f + __expf(-g1))), G + (size_t)rl * (FF / 2));
;       if constexpr ((idx & 7) == 7) __builtin_amdgcn_sched_barrier(0);
;     });
	v_mul_f32_e32 v236, v100, v168
	v_rcp_f32_e32 v209, v209
	v_mul_f32_e32 v237, v112, v168
	v_rcp_f32_e32 v210, v210
	v_mul_f32_e32 v238, v101, v169
	v_rcp_f32_e32 v211, v211
	v_mul_f32_e32 v239, v113, v169
	v_mul_f32_e32 v212, v212, v204
	v_mul_f32_e32 v213, v213, v205
	v_mul_f32_e32 v214, v214, v206
	v_mul_f32_e32 v215, v215, v207
	s_add_u32 s4, s24, 0x0
	s_addc_u32 s5, s25, 0
	v_mul_f32_e32 v216, v216, v208
	v_mul_f32_e32 v217, v217, v209
	v_mul_f32_e32 v218, v218, v210
	v_mul_f32_e32 v219, v219, v211
	v_cvt_pk_bf16_f32 v220, v212, v213
	v_cvt_pk_bf16_f32 v221, v214, v215
	v_cvt_pk_bf16_f32 v222, v216, v217
	v_cvt_pk_bf16_f32 v223, v218, v219
	global_store_dword v196, v220, s[4:5]
	s_add_u32 s4, s4, 0x2c00
	s_addc_u32 s5, s5, 0
	global_store_dword v196, v221, s[4:5]
	s_add_u32 s4, s4, 0x2c00
	s_addc_u32 s5, s5, 0
	global_store_dword v196, v222, s[4:5]
	s_add_u32 s4, s4, 0x2c00
	s_addc_u32 s5, s5, 0
	global_store_dword v196, v223, s[4:5]
	v_exp_f32_e32 v232, v232
	v_mul_f32_e32 v212, v98, v102
	v_exp_f32_e32 v233, v233
	v_mul_f32_e32 v213, v110, v106
	v_exp_f32_e32 v234, v234
	v_mul_f32_e32 v214, v99, v103
	v_exp_f32_e32 v235, v235
	v_mul_f32_e32 v215, v111, v107
	v_exp_f32_e32 v236, v236
	v_mul_f32_e32 v216, v100, v104
	v_exp_f32_e32 v237, v237
	v_mul_f32_e32 v217, v112, v108
	v_exp_f32_e32 v238, v238
	v_mul_f32_e32 v218, v101, v105
	v_exp_f32_e32 v239, v239
	v_mul_f32_e32 v219, v113, v109
	v_fma_f32 v232, v232, v134, v134
	v_fma_f32 v233, v233, v134, v134
	v_fma_f32 v234, v234, v135, v135
	v_fma_f32 v235, v235, v135, v135
	v_fma_f32 v236, v236, v136, v136
	v_fma_f32 v237, v237, v136, v136
	v_fma_f32 v238, v238, v137, v137
	v_fma_f32 v239, v239, v137, v137
	v_rcp_f32_e32 v232, v232
	v_mul_f32_e32 v204, v82, v170
	v_rcp_f32_e32 v233, v233
	v_mul_f32_e32 v205, v94, v170
	v_rcp_f32_e32 v234, v234
	v_mul_f32_e32 v206, v83, v171
	v_rcp_f32_e32 v235, v235
	v_mul_f32_e32 v207, v95, v171
	v_rcp_f32_e32 v236, v236
	v_mul_f32_e32 v208, v84, v172
	v_rcp_f32_e32 v237, v237
	v_mul_f32_e32 v209, v96, v172
	v_rcp_f32_e32 v238, v238
	v_mul_f32_e32 v210, v85, v173
	v_rcp_f32_e32 v239, v239
	v_mul_f32_e32 v211, v97, v173
	v_mul_f32_e32 v212, v212, v232
	v_mul_f32_e32 v213, v213, v233
	v_mul_f32_e32 v214, v214, v234
	v_mul_f32_e32 v215, v215, v235
	s_add_u32 s4, s24, 0x2c000
	s_addc_u32 s5, s25, 0
	v_mul_f32_e32 v216, v216, v236
	v_mul_f32_e32 v217, v217, v237
	v_mul_f32_e32 v218, v218, v238
	v_mul_f32_e32 v219, v219, v239
	v_cvt_pk_bf16_f32 v220, v212, v213
	v_cvt_pk_bf16_f32 v221, v214, v215
	v_cvt_pk_bf16_f32 v222, v216, v217
	v_cvt_pk_bf16_f32 v223, v218, v219
	global_store_dword v196, v220, s[4:5]
	s_add_u32 s4, s4, 0x2c00
	s_addc_u32 s5, s5, 0
	global_store_dword v196, v221, s[4:5]
	s_add_u32 s4, s4, 0x2c00
	s_addc_u32 s5, s5, 0
	global_store_dword v196, v222, s[4:5]
	s_add_u32 s4, s4, 0x2c00
	s_addc_u32 s5, s5, 0
	global_store_dword v196, v223, s[4:5]
	v_exp_f32_e32 v204, v204
	v_mul_f32_e32 v212, v82, v86
	v_exp_f32_e32 v205, v205
	v_mul_f32_e32 v213, v94, v90
	v_exp_f32_e32 v206, v206
	v_mul_f32_e32 v214, v83, v87
	v_exp_f32_e32 v207, v207
	v_mul_f32_e32 v215, v95, v91
	v_exp_f32_e32 v208, v208
	v_mul_f32_e32 v216, v84, v88
	v_exp_f32_e32 v209, v209
	v_mul_f32_e32 v217, v96, v92
	v_exp_f32_e32 v210, v210
	v_mul_f32_e32 v218, v85, v89
	v_exp_f32_e32 v211, v211
	v_mul_f32_e32 v219, v97, v93
	v_fma_f32 v204, v204, v138, v138
	v_fma_f32 v205, v205, v138, v138
	v_fma_f32 v206, v206, v139, v139
	v_fma_f32 v207, v207, v139, v139
	v_fma_f32 v208, v208, v140, v140
	v_fma_f32 v209, v209, v140, v140
	v_fma_f32 v210, v210, v141, v141
	v_fma_f32 v211, v211, v141, v141
	v_rcp_f32_e32 v204, v204
	v_mul_f32_e32 v232, v66, v174
	v_rcp_f32_e32 v205, v205
	v_mul_f32_e32 v233, v78, v174
	v_rcp_f32_e32 v206, v206
	v_mul_f32_e32 v234, v67, v175
	v_rcp_f32_e32 v207, v207
	v_mul_f32_e32 v235, v79, v175
	v_rcp_f32_e32 v208, v208
	v_mul_f32_e32 v236, v68, v176
	v_rcp_f32_e32 v209, v209
	v_mul_f32_e32 v237, v80, v176
	v_rcp_f32_e32 v210, v210
	v_mul_f32_e32 v238, v69, v177
	v_rcp_f32_e32 v211, v211
	v_mul_f32_e32 v239, v81, v177
	v_mul_f32_e32 v212, v212, v204
	v_mul_f32_e32 v213, v213, v205
	v_mul_f32_e32 v214, v214, v206
	v_mul_f32_e32 v215, v215, v207
	s_add_u32 s4, s24, 0x58000
	s_addc_u32 s5, s25, 0
	v_mul_f32_e32 v216, v216, v208
	v_mul_f32_e32 v217, v217, v209
	v_mul_f32_e32 v218, v218, v210
	v_mul_f32_e32 v219, v219, v211
	v_cvt_pk_bf16_f32 v220, v212, v213
	v_cvt_pk_bf16_f32 v221, v214, v215
	v_cvt_pk_bf16_f32 v222, v216, v217
	v_cvt_pk_bf16_f32 v223, v218, v219
	global_store_dword v196, v220, s[4:5]
	s_add_u32 s4, s4, 0x2c00
	s_addc_u32 s5, s5, 0
	global_store_dword v196, v221, s[4:5]
	s_add_u32 s4, s4, 0x2c00
	s_addc_u32 s5, s5, 0
	global_store_dword v196, v222, s[4:5]
	s_add_u32 s4, s4, 0x2c00
	s_addc_u32 s5, s5, 0
	global_store_dword v196, v223, s[4:5]
	v_exp_f32_e32 v232, v232
	v_mul_f32_e32 v212, v66, v70
	v_exp_f32_e32 v233, v233
	v_mul_f32_e32 v213, v78, v74
	v_exp_f32_e32 v234, v234
	v_mul_f32_e32 v214, v67, v71
	v_exp_f32_e32 v235, v235
	v_mul_f32_e32 v215, v79, v75
	v_exp_f32_e32 v236, v236
	v_mul_f32_e32 v216, v68, v72
	v_exp_f32_e32 v237, v237
	v_mul_f32_e32 v217, v80, v76
	v_exp_f32_e32 v238, v238
	v_mul_f32_e32 v218, v69, v73
	v_exp_f32_e32 v239, v239
	v_mul_f32_e32 v219, v81, v77
	v_fma_f32 v232, v232, v142, v142
	v_fma_f32 v233, v233, v142, v142
	v_fma_f32 v234, v234, v143, v143
	v_fma_f32 v235, v235, v143, v143
	v_fma_f32 v236, v236, v144, v144
	v_fma_f32 v237, v237, v144, v144
	v_fma_f32 v238, v238, v145, v145
	v_fma_f32 v239, v239, v145, v145
	v_rcp_f32_e32 v232, v232
	v_mul_f32_e32 v204, v50, v178
	v_rcp_f32_e32 v233, v233
	v_mul_f32_e32 v205, v62, v178
; __device__ __forceinline__ float fdiv(float a, float b) { return a * __builtin_amdgcn_rcpf(b); }
; __device__ __forceinline__ void gemm_tile(const Params& P, const GArgs& ga, const TileDesc& td, int wid_s) {
;     ...
;     static_for<32>([&](auto ic) __attribute__((always_inline)) {
;       EPI_IDX;
;       const float rs = rsv[idx];
;       float g0 = rs * acc[ai][0][m][0][j], u0 = rs * acc[ai][0][m][1][j];
;       float g1 = rs * acc[ai][1][m][0][j], u1 = rs * acc[ai][1][m][1][j];
;       __builtin_nontemporal_store(pack2(fdiv(g0 * u0, 1.f + __expf(-g0)), fdiv(g1 * u1, 1.f + __expf(-g1))), G + (size_t)rl * (FF / 2));
;       if constexpr ((idx & 7) == 7) __builtin_amdgcn_sched_barrier(0);
;     });
	v_rcp_f32_e32 v234, v234
	v_mul_f32_e32 v206, v51, v179
	v_rcp_f32_e32 v235, v235
	v_mul_f32_e32 v207, v63, v179
	v_rcp_f32_e32 v236, v236
	v_mul_f32_e32 v208, v52, v180
	v_rcp_f32_e32 v237, v237
	v_mul_f32_e32 v209, v64, v180
	v_rcp_f32_e32 v238, v238
	v_mul_f32_e32 v210, v53, v181
	v_rcp_f32_e32 v239, v239
	v_mul_f32_e32 v211, v65, v181
	v_mul_f32_e32 v212, v212, v232
	v_mul_f32_e32 v213, v213, v233
	v_mul_f32_e32 v214, v214, v234
	v_mul_f32_e32 v215, v215, v235
	s_add_u32 s4, s24, 0x84000
	s_addc_u32 s5, s25, 0
	v_mul_f32_e32 v216, v216, v236
	v_mul_f32_e32 v217, v217, v237
	v_mul_f32_e32 v218, v218, v238
	v_mul_f32_e32 v219, v219, v239
	v_cvt_pk_bf16_f32 v220, v212, v213
	v_cvt_pk_bf16_f32 v221, v214, v215
	v_cvt_pk_bf16_f32 v222, v216, v217
	v_cvt_pk_bf16_f32 v223, v218, v219
	global_store_dword v196, v220, s[4:5]
	s_add_u32 s4, s4, 0x2c00
	s_addc_u32 s5, s5, 0
	global_store_dword v196, v221, s[4:5]
	s_add_u32 s4, s4, 0x2c00
	s_addc_u32 s5, s5, 0
	global_store_dword v196, v222, s[4:5]
	s_add_u32 s4, s4, 0x2c00
	s_addc_u32 s5, s5, 0
	global_store_dword v196, v223, s[4:5]
	v_exp_f32_e32 v204, v204
	v_mul_f32_e32 v212, v50, v54
	v_exp_f32_e32 v205, v205
	v_mul_f32_e32 v213, v62, v58
	v_exp_f32_e32 v206, v206
	v_mul_f32_e32 v214, v51, v55
	v_exp_f32_e32 v207, v207
	v_mul_f32_e32 v215, v63, v59
	v_exp_f32_e32 v208, v208
	v_mul_f32_e32 v216, v52, v56
	v_exp_f32_e32 v209, v209
	v_mul_f32_e32 v217, v64, v60
	v_exp_f32_e32 v210, v210
	v_mul_f32_e32 v218, v53, v57
	v_exp_f32_e32 v211, v211
	v_mul_f32_e32 v219, v65, v61
	v_fma_f32 v204, v204, v146, v146
	v_fma_f32 v205, v205, v146, v146
	v_fma_f32 v206, v206, v147, v147
	v_fma_f32 v207, v207, v147, v147
	v_fma_f32 v208, v208, v148, v148
	v_fma_f32 v209, v209, v148, v148
	v_fma_f32 v210, v210, v149, v149
	v_fma_f32 v211, v211, v149, v149
	v_rcp_f32_e32 v204, v204
	v_mul_f32_e32 v232, v34, v182
	v_rcp_f32_e32 v205, v205
	v_mul_f32_e32 v233, v46, v182
	v_rcp_f32_e32 v206, v206
	v_mul_f32_e32 v234, v35, v183
	v_rcp_f32_e32 v207, v207
	v_mul_f32_e32 v235, v47, v183
	v_rcp_f32_e32 v208, v208
	v_mul_f32_e32 v236, v36, v184
	v_rcp_f32_e32 v209, v209
	v_mul_f32_e32 v237, v48, v184
	v_rcp_f32_e32 v210, v210
	v_mul_f32_e32 v238, v37, v185
	v_rcp_f32_e32 v211, v211
	v_mul_f32_e32 v239, v49, v185
	v_mul_f32_e32 v212, v212, v204
	v_mul_f32_e32 v213, v213, v205
	v_mul_f32_e32 v214, v214, v206
	v_mul_f32_e32 v215, v215, v207
	s_add_u32 s4, s24, 0x160000
	s_addc_u32 s5, s25, 0
	v_mul_f32_e32 v216, v216, v208
	v_mul_f32_e32 v217, v217, v209
	v_mul_f32_e32 v218, v218, v210
	v_mul_f32_e32 v219, v219, v211
	v_cvt_pk_bf16_f32 v220, v212, v213
	v_cvt_pk_bf16_f32 v221, v214, v215
	v_cvt_pk_bf16_f32 v222, v216, v217
	v_cvt_pk_bf16_f32 v223, v218, v219
	global_store_dword v196, v220, s[4:5]
	s_add_u32 s4, s4, 0x2c00
	s_addc_u32 s5, s5, 0
	global_store_dword v196, v221, s[4:5]
	s_add_u32 s4, s4, 0x2c00
	s_addc_u32 s5, s5, 0
	global_store_dword v196, v222, s[4:5]
	s_add_u32 s4, s4, 0x2c00
	s_addc_u32 s5, s5, 0
	global_store_dword v196, v223, s[4:5]
	v_exp_f32_e32 v232, v232
	v_mul_f32_e32 v212, v34, v38
	v_exp_f32_e32 v233, v233
	v_mul_f32_e32 v213, v46, v42
	v_exp_f32_e32 v234, v234
	v_mul_f32_e32 v214, v35, v39
	v_exp_f32_e32 v235, v235
	v_mul_f32_e32 v215, v47, v43
	v_exp_f32_e32 v236, v236
	v_mul_f32_e32 v216, v36, v40
	v_exp_f32_e32 v237, v237
	v_mul_f32_e32 v217, v48, v44
	v_exp_f32_e32 v238, v238
	v_mul_f32_e32 v218, v37, v41
	v_exp_f32_e32 v239, v239
	v_mul_f32_e32 v219, v49, v45
	v_fma_f32 v232, v232, v150, v150
	v_fma_f32 v233, v233, v150, v150
	v_fma_f32 v234, v234, v151, v151
	v_fma_f32 v235, v235, v151, v151
	v_fma_f32 v236, v236, v152, v152
	v_fma_f32 v237, v237, v152, v152
	v_fma_f32 v238, v238, v153, v153
	v_fma_f32 v239, v239, v153, v153
	v_rcp_f32_e32 v232, v232
	v_mul_f32_e32 v204, v18, v186
	v_rcp_f32_e32 v233, v233
	v_mul_f32_e32 v205, v30, v186
	v_rcp_f32_e32 v234, v234
	v_mul_f32_e32 v206, v19, v187
	v_rcp_f32_e32 v235, v235
	v_mul_f32_e32 v207, v31, v187
	v_rcp_f32_e32 v236, v236
	v_mul_f32_e32 v208, v20, v188
	v_rcp_f32_e32 v237, v237
	v_mul_f32_e32 v209, v32, v188
	v_rcp_f32_e32 v238, v238
	v_mul_f32_e32 v210, v21, v189
	v_rcp_f32_e32 v239, v239
	v_mul_f32_e32 v211, v33, v189
	v_mul_f32_e32 v212, v212, v232
	v_mul_f32_e32 v213, v213, v233
	v_mul_f32_e32 v214, v214, v234
; __device__ __forceinline__ float fdiv(float a, float b) { return a * __builtin_amdgcn_rcpf(b); }
; __device__ __forceinline__ void gemm_tile(const Params& P, const GArgs& ga, const TileDesc& td, int wid_s) {
;     ...
;     static_for<32>([&](auto ic) __attribute__((always_inline)) {
;       EPI_IDX;
;       const float rs = rsv[idx];
;       float g0 = rs * acc[ai][0][m][0][j], u0 = rs * acc[ai][0][m][1][j];
;       float g1 = rs * acc[ai][1][m][0][j], u1 = rs * acc[ai][1][m][1][j];
;       __builtin_nontemporal_store(pack2(fdiv(g0 * u0, 1.f + __expf(-g0)), fdiv(g1 * u1, 1.f + __expf(-g1))), G + (size_t)rl * (FF / 2));
;       if constexpr ((idx & 7) == 7) __builtin_amdgcn_sched_barrier(0);
;     });
	v_mul_f32_e32 v215, v215, v235
	s_add_u32 s4, s24, 0x18c000
	s_addc_u32 s5, s25, 0
	v_mul_f32_e32 v216, v216, v236
	v_mul_f32_e32 v217, v217, v237
	v_mul_f32_e32 v218, v218, v238
	v_mul_f32_e32 v219, v219, v239
	v_cvt_pk_bf16_f32 v220, v212, v213
	v_cvt_pk_bf16_f32 v221, v214, v215
	v_cvt_pk_bf16_f32 v222, v216, v217
	v_cvt_pk_bf16_f32 v223, v218, v219
	global_store_dword v196, v220, s[4:5]
	s_add_u32 s4, s4, 0x2c00
	s_addc_u32 s5, s5, 0
	global_store_dword v196, v221, s[4:5]
	s_add_u32 s4, s4, 0x2c00
	s_addc_u32 s5, s5, 0
	global_store_dword v196, v222, s[4:5]
	s_add_u32 s4, s4, 0x2c00
	s_addc_u32 s5, s5, 0
	global_store_dword v196, v223, s[4:5]
	v_exp_f32_e32 v204, v204
	v_mul_f32_e32 v212, v18, v22
	v_exp_f32_e32 v205, v205
	v_mul_f32_e32 v213, v30, v26
	v_exp_f32_e32 v206, v206
	v_mul_f32_e32 v214, v19, v23
	v_exp_f32_e32 v207, v207
	v_mul_f32_e32 v215, v31, v27
	v_exp_f32_e32 v208, v208
	v_mul_f32_e32 v216, v20, v24
	v_exp_f32_e32 v209, v209
	v_mul_f32_e32 v217, v32, v28
	v_exp_f32_e32 v210, v210
	v_mul_f32_e32 v218, v21, v25
	v_exp_f32_e32 v211, v211
	v_mul_f32_e32 v219, v33, v29
	v_fma_f32 v204, v204, v154, v154
	v_fma_f32 v205, v205, v154, v154
	v_fma_f32 v206, v206, v155, v155
	v_fma_f32 v207, v207, v155, v155
	v_fma_f32 v208, v208, v156, v156
	v_fma_f32 v209, v209, v156, v156
	v_fma_f32 v210, v210, v157, v157
	v_fma_f32 v211, v211, v157, v157
	v_rcp_f32_e32 v204, v204
	v_mul_f32_e32 v232, v2, v190
	v_rcp_f32_e32 v205, v205
	v_mul_f32_e32 v233, v14, v190
	v_rcp_f32_e32 v206, v206
	v_mul_f32_e32 v234, v3, v191
	v_rcp_f32_e32 v207, v207
	v_mul_f32_e32 v235, v15, v191
	v_rcp_f32_e32 v208, v208
	v_mul_f32_e32 v236, v4, v192
	v_rcp_f32_e32 v209, v209
	v_mul_f32_e32 v237, v16, v192
	v_rcp_f32_e32 v210, v210
	v_mul_f32_e32 v238, v5, v193
	v_rcp_f32_e32 v211, v211
	v_mul_f32_e32 v239, v17, v193
	v_mul_f32_e32 v212, v212, v204
	v_mul_f32_e32 v213, v213, v205
	v_mul_f32_e32 v214, v214, v206
	v_mul_f32_e32 v215, v215, v207
	s_add_u32 s4, s24, 0x1b8000
	s_addc_u32 s5, s25, 0
	v_mul_f32_e32 v216, v216, v208
	v_mul_f32_e32 v217, v217, v209
	v_mul_f32_e32 v218, v218, v210
	v_mul_f32_e32 v219, v219, v211
	v_cvt_pk_bf16_f32 v220, v212, v213
	v_cvt_pk_bf16_f32 v221, v214, v215
	v_cvt_pk_bf16_f32 v222, v216, v217
	v_cvt_pk_bf16_f32 v223, v218, v219
	global_store_dword v196, v220, s[4:5]
	s_add_u32 s4, s4, 0x2c00
	s_addc_u32 s5, s5, 0
	global_store_dword v196, v221, s[4:5]
	s_add_u32 s4, s4, 0x2c00
	s_addc_u32 s5, s5, 0
	global_store_dword v196, v222, s[4:5]
	s_add_u32 s4, s4, 0x2c00
	s_addc_u32 s5, s5, 0
	global_store_dword v196, v223, s[4:5]
	v_exp_f32_e32 v232, v232
	v_mul_f32_e32 v212, v2, v6
	v_exp_f32_e32 v233, v233
	v_mul_f32_e32 v213, v14, v10
	v_exp_f32_e32 v234, v234
	v_mul_f32_e32 v214, v3, v7
	v_exp_f32_e32 v235, v235
	v_mul_f32_e32 v215, v15, v11
	v_exp_f32_e32 v236, v236
	v_mul_f32_e32 v216, v4, v8
	v_exp_f32_e32 v237, v237
	v_mul_f32_e32 v217, v16, v12
	v_exp_f32_e32 v238, v238
	v_mul_f32_e32 v218, v5, v9
	v_exp_f32_e32 v239, v239
	v_mul_f32_e32 v219, v17, v13
	v_fma_f32 v232, v232, v158, v158
	v_fma_f32 v233, v233, v158, v158
	v_fma_f32 v234, v234, v159, v159
	v_fma_f32 v235, v235, v159, v159
	v_fma_f32 v236, v236, v160, v160
	v_fma_f32 v237, v237, v160, v160
	v_fma_f32 v238, v238, v161, v161
	v_fma_f32 v239, v239, v161, v161
	v_rcp_f32_e32 v232, v232
	s_nop 0
	v_rcp_f32_e32 v233, v233
	v_rcp_f32_e32 v234, v234
	v_rcp_f32_e32 v235, v235
	v_rcp_f32_e32 v236, v236
	v_rcp_f32_e32 v237, v237
	v_rcp_f32_e32 v238, v238
	v_rcp_f32_e32 v239, v239
	v_mul_f32_e32 v212, v212, v232
	v_mul_f32_e32 v213, v213, v233
	v_mul_f32_e32 v214, v214, v234
	v_mul_f32_e32 v215, v215, v235
	s_add_u32 s4, s24, 0x1e4000
	s_addc_u32 s5, s25, 0
	v_mul_f32_e32 v216, v216, v236
	v_mul_f32_e32 v217, v217, v237
	v_mul_f32_e32 v218, v218, v238
	v_mul_f32_e32 v219, v219, v239
	v_cvt_pk_bf16_f32 v220, v212, v213
	v_cvt_pk_bf16_f32 v221, v214, v215
	v_cvt_pk_bf16_f32 v222, v216, v217
	v_cvt_pk_bf16_f32 v223, v218, v219
	global_store_dword v196, v220, s[4:5]
	s_add_u32 s4, s4, 0x2c00
	s_addc_u32 s5, s5, 0
	global_store_dword v196, v221, s[4:5]
	s_add_u32 s4, s4, 0x2c00
	s_addc_u32 s5, s5, 0
	global_store_dword v196, v222, s[4:5]
	s_add_u32 s4, s4, 0x2c00
	s_addc_u32 s5, s5, 0
	global_store_dword v196, v223, s[4:5]
	s_branch .LBB0_290
